# m6 plus: sample-seq state prefetch moved after the conv part, incremental A-prefetch addresses and DPP butterfly in the scan
# baseline (speedup 1.0000x reference)
.LBB0_845:
	s_or_b64 exec, exec, s[14:15]
	s_lshl_b32 s14, s47, 5
	s_lshl_b64 s[12:13], s[12:13], 2
	s_add_u32 s12, s28, s12
	s_addc_u32 s13, s29, s13
	global_load_dword v120, v125, s[12:13]
	v_add_u32_e32 v41, 0, v124
	v_mul_lo_u32 v52, v28, s63
	v_add_u32_e32 v129, v41, v52
	ds_write_b128 v129, v[0:3]
	v_mul_lo_u32 v0, v30, s63
	s_or_b32 s12, s14, 1
	v_add_u32_e32 v173, v41, v0
	v_mul_lo_u32 v0, v32, s63
	s_lshl_b32 s47, s12, 6
	s_lshl_b32 s12, s12, 3
	v_lshlrev_b32_e32 v39, 3, v46
	v_add_u32_e32 v174, v41, v0
	v_mul_lo_u32 v0, v34, s63
	s_or_b32 s12, s12, s35
	v_add_u32_e32 v175, v41, v0
	v_mul_lo_u32 v1, v36, s64
	v_lshlrev_b32_e32 v0, 1, v39
	v_lshl_add_u32 v2, v51, 1, 0
	s_ashr_i32 s13, s12, 31
	v_add3_u32 v176, 0, v1, v0
	v_add_u32_e32 v177, v2, v1
	v_lshrrev_b32_e32 v1, 3, v37
	s_sub_i32 s51, s47, 64
	s_lshl_b64 s[14:15], s[12:13], 14
	v_mul_lo_u32 v1, v1, s64
	s_add_u32 s14, s20, s14
	v_add_u32_e32 v178, v2, v1
	s_addc_u32 s15, s21, s15
	ds_write_b128 v173, v[4:7]
	ds_write_b128 v174, v[8:11]
	s_waitcnt vmcnt(4)
	ds_write_b128 v175, v[12:15]
	s_waitcnt vmcnt(3)
	ds_write_b128 v176, v[16:19] offset:34816
	s_waitcnt vmcnt(2)
	ds_write_b128 v177, v[24:27] offset:44032
	s_waitcnt vmcnt(1)
	ds_write_b128 v178, v[20:23] offset:44032
	s_and_saveexec_b64 s[52:53], s[16:17]
	s_xor_b64 s[52:53], exec, s[52:53]
	v_add_u32_e32 v1, s51, v28
	v_mad_i64_i32 v[4:5], s[70:71], v1, s60, v[126:127]
	s_or_saveexec_b64 s[52:53], s[52:53]
	v_lshl_add_u64 v[2:3], s[14:15], 0, v[124:125]
	s_xor_b64 exec, exec, s[52:53]
	v_lshlrev_b64 v[4:5], 8, v[28:29]
	v_lshl_add_u64 v[4:5], v[2:3], 0, v[4:5]
	s_or_b64 exec, exec, s[52:53]
	global_load_dwordx4 v[80:83], v[4:5], off
	v_lshl_add_u64 v[222:223], v[4:5], 0, s[42:43]
	s_and_saveexec_b64 s[14:15], s[4:5]
	s_xor_b64 s[14:15], exec, s[14:15]
	v_add_u32_e32 v1, s51, v30
	v_mad_i64_i32 v[4:5], s[52:53], v1, s60, v[126:127]
	s_andn2_saveexec_b64 s[14:15], s[14:15]
	v_lshlrev_b64 v[4:5], 8, v[30:31]
	v_lshl_add_u64 v[4:5], v[2:3], 0, v[4:5]
	s_or_b64 exec, exec, s[14:15]
	global_load_dwordx4 v[84:87], v[4:5], off
	v_lshl_add_u64 v[224:225], v[4:5], 0, s[42:43]
	s_and_saveexec_b64 s[14:15], s[6:7]
	s_xor_b64 s[14:15], exec, s[14:15]
	v_add_u32_e32 v1, s51, v32
	v_mad_i64_i32 v[4:5], s[52:53], v1, s60, v[126:127]
	s_andn2_saveexec_b64 s[14:15], s[14:15]
	v_lshlrev_b64 v[4:5], 8, v[32:33]
	v_lshl_add_u64 v[4:5], v[2:3], 0, v[4:5]
	s_or_b64 exec, exec, s[14:15]
	global_load_dwordx4 v[92:95], v[4:5], off
	v_lshl_add_u64 v[226:227], v[4:5], 0, s[40:41]
	s_and_saveexec_b64 s[14:15], s[8:9]
	s_xor_b64 s[14:15], exec, s[14:15]
	v_add_u32_e32 v1, s51, v34
	v_mov_b32_e32 v35, v125
	v_mad_i64_i32 v[4:5], s[52:53], v1, s60, v[126:127]
	v_lshlrev_b64 v[146:147], 8, v[34:35]
	s_andn2_saveexec_b64 s[14:15], s[14:15]
	v_lshlrev_b64 v[146:147], 8, v[34:35]
	v_lshl_add_u64 v[4:5], v[2:3], 0, v[146:147]
	s_or_b64 exec, exec, s[14:15]
	s_and_b32 s35, s69, 7
	s_lshl_b32 s52, s35, 8
	s_lshl_b64 s[12:13], s[12:13], 13
	s_add_u32 s12, s22, s12
	s_addc_u32 s13, s23, s13
	v_lshlrev_b64 v[2:3], 1, v[44:45]
	global_load_dwordx4 v[104:107], v[4:5], off
	v_lshl_add_u64 v[228:229], v[4:5], 0, s[40:41]
	v_lshl_add_u64 v[4:5], s[12:13], 0, v[2:3]
	v_mov_b32_e32 v1, v125
	v_lshl_add_u64 v[4:5], v[4:5], 0, v[0:1]
	global_load_dwordx4 v[88:91], v[4:5], off
	v_add_u32_e32 v6, s47, v28
	v_mov_b64_e32 v[4:5], s[18:19]
	v_mad_i64_i32 v[6:7], s[12:13], v6, s60, v[4:5]
	v_add_u32_e32 v9, s47, v30
	v_lshl_add_u64 v[6:7], v[6:7], 0, s[36:37]
	v_mov_b32_e32 v39, v125
	v_mad_i64_i32 v[4:5], s[12:13], v9, s60, v[4:5]
	v_lshl_add_u64 v[6:7], v[6:7], 0, v[38:39]
	v_mov_b32_e32 v41, v125
	v_lshl_add_u64 v[4:5], v[4:5], 0, s[36:37]
	v_lshl_add_u64 v[6:7], v[6:7], 0, v[40:41]
	v_lshl_add_u64 v[4:5], v[4:5], 0, v[38:39]
	v_lshl_add_u64 v[4:5], v[4:5], 0, v[40:41]
	global_load_dwordx4 v[96:99], v[6:7], off offset:2048
	global_load_dwordx4 v[100:103], v[4:5], off offset:2048
	v_ashrrev_i32_e32 v8, 8, v47
	v_lshl_add_u64 v[2:3], s[22:23], 0, v[2:3]
	s_add_i32 s34, s34, s35
	v_lshlrev_b32_e32 v179, 6, v8
	v_lshl_add_u64 v[160:161], v[2:3], 0, v[0:1]
	v_lshl_add_u64 v[0:1], s[48:49], 0, v[38:39]
	s_add_i32 s48, s34, 16
	s_ashr_i32 s51, s50, 31
	v_or_b32_e32 v7, v179, v48
	v_lshl_add_u64 v[162:163], v[0:1], 0, v[40:41]
	v_add_u16_e32 v0, v43, v48
	s_add_u32 s34, s18, s52
	v_ashrrev_i32_e32 v37, 31, v36
	v_lshlrev_b32_e32 v6, 4, v49
	v_mul_lo_u32 v4, v7, s63
	v_mul_lo_u32 v7, v7, s64
	v_lshrrev_b16_e32 v0, 1, v0
	s_addc_u32 s35, s19, 0
	v_mad_u32_u24 v5, v50, s63, 0
	v_add3_u32 v183, 0, v7, v6
	v_mul_u32_u24_e32 v7, 0x90, v48
	v_add3_u32 v205, v0, s50, 64
	v_lshl_add_u64 v[0:1], v[36:37], 0, s[50:51]
	v_mov_b64_e32 v[2:3], s[34:35]
	v_add_u32_e32 v180, v5, v6
	v_add3_u32 v181, 0, v4, v6
	v_add3_u32 v184, 0, v7, v6
	v_lshlrev_b32_e32 v6, 7, v8
	v_mad_u64_u32 v[166:167], s[34:35], v0, s60, v[2:3]
	v_add3_u32 v185, v5, v6, v128
	v_mul_u32_u24_e32 v6, 0x210, v49
	s_add_u32 s34, s55, s52
	s_waitcnt lgkmcnt(0)
	s_barrier
	v_lshlrev_b32_e32 v4, 6, v47
	v_lshlrev_b32_e32 v150, 2, v50
	v_lshlrev_b32_e32 v6, 2, v6
	v_mad_i32_i24 v167, v1, s60, v167
	v_lshlrev_b64 v[0:1], 11, v[0:1]
	s_addc_u32 s35, s56, 0
	v_lshl_add_u32 v9, v42, 2, s65
	v_and_b32_e32 v4, 64, v4
	v_mul_u32_u24_e32 v10, 0x90, v50
	v_mul_lo_u32 v5, v36, s67
	v_add3_u32 v186, s65, v150, v6
	v_lshl_add_u64 v[168:169], s[34:35], 0, v[0:1]
	v_mov_b32_e32 v0, 0
	v_lshlrev_b32_e32 v148, 2, v49
	v_add3_u32 v182, s66, v10, v128
	v_cmp_eq_u32_e64 s[12:13], 1, v8
	v_cmp_ne_u32_e64 s[14:15], 1, v8
	v_lshlrev_b64 v[152:153], 8, v[28:29]
	v_lshlrev_b64 v[154:155], 8, v[30:31]
	v_lshlrev_b64 v[156:157], 8, v[32:33]
	v_add3_u32 v187, s65, v6, v150
	v_add_u32_e32 v188, 0x210, v186
	v_add_u32_e32 v189, 0x420, v186
	v_add_u32_e32 v190, 0x630, v186
	v_add_u32_e32 v191, 0x1080, v186
	v_add_u32_e32 v192, 0x1290, v186
	v_add_u32_e32 v193, 0x14a0, v186
	v_add_u32_e32 v194, 0x16b0, v186
	v_add_u32_e32 v195, 0x2100, v186
	v_add_u32_e32 v196, 0x2310, v186
	v_add_u32_e32 v197, 0x2520, v186
	v_add_u32_e32 v198, 0x2730, v186
	v_add_u32_e32 v199, 0x3180, v186
	v_add_u32_e32 v200, 0x3390, v186
	v_add_u32_e32 v201, 0x35a0, v186
	v_add_u32_e32 v202, 0x37b0, v186
	v_lshl_add_u64 v[158:159], s[20:21], 0, v[124:125]
	v_add3_u32 v203, v34, s50, 64
	v_add3_u32 v204, v32, s50, 64
	v_lshlrev_b32_e32 v164, 5, v46
	v_mov_b32_e32 v165, v125
	s_mov_b32 s47, 0
	v_lshlrev_b32_e32 v124, 1, v4
	v_add_u32_e32 v206, v9, v5
	s_mov_b32 s70, 0
	v_mov_b32_e32 v1, v0
	v_mov_b32_e32 v2, v0
	v_mov_b32_e32 v3, v0
	v_mov_b32_e32 v4, v0
	v_mov_b32_e32 v5, v0
	v_mov_b32_e32 v6, v0
	v_mov_b32_e32 v7, v0
	v_mov_b32_e32 v8, v0
	v_mov_b32_e32 v9, v0
	v_mov_b32_e32 v10, v0
	v_mov_b32_e32 v11, v0
	v_mov_b32_e32 v12, v0
	v_mov_b32_e32 v13, v0
	v_mov_b32_e32 v14, v0
	v_mov_b32_e32 v15, v0
	v_mov_b32_e32 v16, v0
	v_mov_b32_e32 v17, v0
	v_mov_b32_e32 v18, v0
	v_mov_b32_e32 v19, v0
	v_mov_b32_e32 v20, v0
	v_mov_b32_e32 v21, v0
	v_mov_b32_e32 v22, v0
	v_mov_b32_e32 v23, v0
	v_mov_b32_e32 v24, v0
	v_mov_b32_e32 v25, v0
	v_mov_b32_e32 v26, v0
	v_mov_b32_e32 v27, v0
	v_mov_b32_e32 v28, v0
	v_mov_b32_e32 v29, v0
	v_mov_b32_e32 v30, v0
	v_mov_b32_e32 v31, v0
	s_branch .LBB0_863

.Lmy_scan_faj:
	s_cmp_lt_u32 s70, 30
	s_cbranch_scc0 .LBB0_899
	global_load_dwordx4 v[80:83], v[222:223], off
	global_load_dwordx4 v[84:87], v[224:225], off
	global_load_dwordx4 v[92:95], v[226:227], off
	global_load_dwordx4 v[104:107], v[228:229], off
	v_lshl_add_u64 v[222:223], v[222:223], 0, s[42:43]
	v_lshl_add_u64 v[224:225], v[224:225], 0, s[42:43]
	v_lshl_add_u64 v[226:227], v[226:227], 0, s[40:41]
	v_lshl_add_u64 v[228:229], v[228:229], 0, s[40:41]

.LBB0_901:
	s_or_b64 exec, exec, s[52:53]
	s_waitcnt lgkmcnt(0)
	s_barrier
	ds_read_b128 v[32:35], v206
	ds_read_b128 v[36:39], v206 offset:16
	ds_read_b128 v[40:43], v206 offset:32
	ds_read_b128 v[44:47], v206 offset:48
	s_waitcnt lgkmcnt(3)
	v_pk_mul_f32 v[48:49], v[34:35], v[34:35]
	v_pk_mul_f32 v[50:51], v[32:33], v[32:33]
	s_nop 0
	v_pk_mov_b32 v[52:53], v[50:51], v[48:49] op_sel:[1,0]
	v_mov_b32_e32 v51, v49
	v_pk_add_f32 v[48:49], v[52:53], v[50:51]
	s_waitcnt lgkmcnt(2)
	v_pk_mul_f32 v[50:51], v[38:39], v[38:39]
	v_pk_mul_f32 v[52:53], v[36:37], v[36:37]
	v_pk_add_f32 v[48:49], v[48:49], v[48:49] op_sel:[0,1] op_sel_hi:[1,0]
	v_pk_mov_b32 v[54:55], v[52:53], v[50:51] op_sel:[1,0]
	v_mov_b32_e32 v53, v51
	v_pk_add_f32 v[50:51], v[54:55], v[52:53]
	s_waitcnt lgkmcnt(0)
	v_mul_f32_e32 v52, v44, v44
	v_mul_f32_e32 v53, v45, v45
	v_pk_add_f32 v[50:51], v[50:51], v[50:51] op_sel:[0,1] op_sel_hi:[1,0]
	v_mov_b32_e32 v49, v52
	v_mov_b32_e32 v51, v53
	v_pk_add_f32 v[48:49], v[48:49], v[50:51]
	v_mul_f32_e32 v50, v41, v41
	v_mul_f32_e32 v52, v43, v43
	v_mul_f32_e32 v54, v46, v46
	v_mul_f32_e32 v55, v47, v47
	v_pk_fma_f32 v[50:51], v[40:41], v[40:41], v[50:51] op_sel_hi:[1,1,0]
	v_pk_fma_f32 v[52:53], v[42:43], v[42:43], v[52:53] op_sel_hi:[1,1,0]
	v_mov_b32_e32 v51, v54
	v_mov_b32_e32 v53, v55
	v_pk_add_f32 v[50:51], v[50:51], v[52:53]
	s_nop 0
	v_pk_add_f32 v[48:49], v[48:49], v[50:51]
	v_add_f32_e32 v48, v48, v49
	s_nop 1
	v_add_f32_dpp v48, v48, v48 quad_perm:[1,0,3,2] row_mask:0xf bank_mask:0xf
	s_nop 1
	v_add_f32_dpp v48, v48, v48 quad_perm:[2,3,0,1] row_mask:0xf bank_mask:0xf
	s_nop 1
	v_add_f32_dpp v48, v48, v48 row_half_mirror row_mask:0xf bank_mask:0xf
	s_cmp_lt_u32 s70, 30
	s_cbranch_scc1 .Lmy_scan_w4
	s_waitcnt vmcnt(0)
	s_branch .Lmy_scan_wj

.Lmy_scan_wj:
	v_and_b32_e32 v51, 0xffff0000, v112
	v_lshlrev_b32_e32 v50, 16, v112
	v_fmamk_f32 v48, v48, 0x3c000000, v171
	v_mul_f32_e32 v49, 0x4b800000, v48
	v_cmp_gt_f32_e32 vcc, s68, v48
	s_nop 1
	v_cndmask_b32_e32 v48, v48, v49, vcc
	v_rsq_f32_e32 v48, v48
	s_nop 0
	v_mul_f32_e32 v49, 0x45800000, v48
	v_cndmask_b32_e32 v48, v48, v49, vcc
	v_pk_mul_f32 v[32:33], v[32:33], v[48:49] op_sel_hi:[1,0]
	v_pk_mul_f32 v[34:35], v[34:35], v[48:49] op_sel_hi:[1,0]
	v_pk_mul_f32 v[32:33], v[76:77], v[32:33]
	v_pk_mul_f32 v[34:35], v[78:79], v[34:35]
	v_pk_mul_f32 v[32:33], v[32:33], v[50:51]
	v_lshlrev_b32_e32 v50, 16, v113
	v_and_b32_e32 v51, 0xffff0000, v113
	v_pk_mul_f32 v[36:37], v[36:37], v[48:49] op_sel_hi:[1,0]
	v_pk_mul_f32 v[34:35], v[34:35], v[50:51]
	v_lshlrev_b32_e32 v50, 16, v114
	v_and_b32_e32 v51, 0xffff0000, v114
	v_pk_mul_f32 v[36:37], v[72:73], v[36:37]
	v_pk_mul_f32 v[38:39], v[38:39], v[48:49] op_sel_hi:[1,0]
	v_pk_mul_f32 v[36:37], v[36:37], v[50:51]
	v_lshlrev_b32_e32 v50, 16, v115
	v_and_b32_e32 v51, 0xffff0000, v115
	v_pk_mul_f32 v[38:39], v[74:75], v[38:39]
	v_pk_mul_f32 v[40:41], v[40:41], v[48:49] op_sel_hi:[1,0]
	v_pk_mul_f32 v[38:39], v[38:39], v[50:51]
	v_lshlrev_b32_e32 v50, 16, v108
	v_and_b32_e32 v51, 0xffff0000, v108
	v_pk_mul_f32 v[40:41], v[68:69], v[40:41]
	v_pk_mul_f32 v[42:43], v[42:43], v[48:49] op_sel_hi:[1,0]
	v_pk_mul_f32 v[40:41], v[40:41], v[50:51]
	v_lshlrev_b32_e32 v50, 16, v109
	v_and_b32_e32 v51, 0xffff0000, v109
	v_pk_mul_f32 v[42:43], v[70:71], v[42:43]
	v_pk_mul_f32 v[44:45], v[44:45], v[48:49] op_sel_hi:[1,0]
	v_pk_mul_f32 v[42:43], v[42:43], v[50:51]
	v_lshlrev_b32_e32 v50, 16, v110
	v_and_b32_e32 v51, 0xffff0000, v110
	v_pk_mul_f32 v[44:45], v[64:65], v[44:45]
	v_pk_mul_f32 v[46:47], v[46:47], v[48:49] op_sel_hi:[1,0]
	v_lshl_add_u64 v[48:49], v[166:167], 0, v[164:165]
	v_pk_mul_f32 v[44:45], v[44:45], v[50:51]
	v_lshlrev_b32_e32 v50, 16, v111
	v_and_b32_e32 v51, 0xffff0000, v111
	v_pk_mul_f32 v[46:47], v[66:67], v[46:47]
	v_cvt_pk_bf16_f32 v32, v32, v33
	v_cvt_pk_bf16_f32 v33, v34, v35
	v_cvt_pk_bf16_f32 v34, v36, v37
	v_add_co_u32_e32 v36, vcc, s62, v48
	v_pk_mul_f32 v[46:47], v[46:47], v[50:51]
	v_cvt_pk_bf16_f32 v35, v38, v39
	v_addc_co_u32_e32 v37, vcc, 0, v49, vcc
	global_store_dwordx4 v[36:37], v[32:35], off
	s_andn2_b64 vcc, exec, s[50:51]
	s_nop 0
	v_cvt_pk_bf16_f32 v32, v40, v41
	v_cvt_pk_bf16_f32 v33, v42, v43
	v_cvt_pk_bf16_f32 v34, v44, v45
	v_cvt_pk_bf16_f32 v35, v46, v47
	global_store_dwordx4 v[36:37], v[32:35], off offset:16
	s_cbranch_vccnz .LBB0_862
	s_cmp_gt_u32 s70, 29
	ds_write_b128 v176, v[88:91] offset:34816
	ds_write_b128 v177, v[96:99] offset:44032
	ds_write_b128 v178, v[100:103] offset:44032
	s_cbranch_scc1 .LBB0_862
	s_ashr_i32 s49, s48, 31
	s_lshl_b64 s[34:35], s[48:49], 13
	v_lshl_add_u64 v[32:33], v[160:161], 0, s[34:35]
	global_load_dwordx4 v[88:91], v[32:33], off
	v_add_u32_e32 v32, s47, v151
	v_add_u32_e32 v32, 0x80, v32
	v_add_u32_e32 v34, s47, v172
	v_mad_i64_i32 v[32:33], s[34:35], v32, s60, v[162:163]
	v_add_u32_e32 v34, 0x80, v34
	v_mad_i64_i32 v[34:35], s[34:35], v34, s60, v[162:163]
	global_load_dwordx4 v[96:99], v[32:33], off offset:2048
	global_load_dwordx4 v[100:103], v[34:35], off offset:2048
	s_branch .LBB0_862

.LBB0_923:
	s_or_b64 exec, exec, s[4:5]
	s_add_u32 s24, s24, s26
	s_waitcnt lgkmcnt(0)
	s_barrier
	s_addc_u32 s25, s25, s27
	s_add_i32 s3, s3, s12
	s_add_i32 s4, s13, s3
	s_waitcnt vmcnt(8)
	v_mov_b64_e32 v[46:47], v[2:3]
	v_mov_b64_e32 v[50:51], v[6:7]
	v_mov_b64_e32 v[54:55], v[10:11]
	v_mov_b64_e32 v[58:59], v[14:15]
	v_mov_b64_e32 v[62:63], v[18:19]
	v_mov_b64_e32 v[66:67], v[22:23]
	v_mov_b64_e32 v[70:71], v[26:27]
	v_mov_b64_e32 v[74:75], v[30:31]
	s_cmpk_lt_i32 s4, 0x400
	v_mov_b64_e32 v[44:45], v[0:1]
	v_mov_b64_e32 v[48:49], v[4:5]
	v_mov_b64_e32 v[52:53], v[8:9]
	v_mov_b64_e32 v[56:57], v[12:13]
	v_mov_b64_e32 v[60:61], v[16:17]
	v_mov_b64_e32 v[64:65], v[20:21]
	v_mov_b64_e32 v[68:69], v[24:25]
	v_mov_b64_e32 v[72:73], v[28:29]
	s_cbranch_scc0 .LBB0_958
.LBB0_924:
	s_add_i32 s4, s33, s3
	v_mov_b32_e32 v143, v170
	s_cmpk_lt_i32 s4, 0x400
	s_cselect_b32 s28, s4, -1
	s_mov_b32 s100, s28
	s_mov_b32 s101, 0
	v_ashrrev_i32_e32 v164, 5, v143
	v_lshlrev_b32_e32 v144, 3, v164
	v_and_b32_e32 v159, 31, v143
	v_ashrrev_i32_e32 v145, 31, v144
.LBB0_926:
	s_add_i32 s4, s13, s3
	s_ashr_i32 s34, s4, 3
	s_lshl_b32 s5, s34, 2
	s_add_i32 s42, s5, 0x4000
	s_and_b32 s35, s4, 7
	s_ashr_i32 s43, s42, 31
	s_lshl_b32 s4, s35, 2
	s_add_u32 s28, s18, s4
	s_addc_u32 s46, s19, 0
	s_lshl_b64 s[4:5], s[42:43], 6
	s_add_u32 s4, s28, s4
	s_addc_u32 s5, s46, s5
	global_load_dword v165, v141, s[4:5] offset:32
	global_load_dword v163, v141, s[4:5] offset:96
	global_load_dword v162, v141, s[4:5] offset:160
	global_load_dword v161, v141, s[4:5] offset:224
	global_load_dword v146, v141, s[4:5] offset:192
	global_load_dword v148, v141, s[4:5] offset:128
	global_load_dword v150, v141, s[4:5] offset:64
	global_load_dword v152, v141, s[4:5]
	v_ashrrev_i32_e32 v142, 4, v143
	s_waitcnt vmcnt(9)
	v_and_or_b32 v32, v142, 3, s42
	v_mov_b32_e32 v33, s43
	v_lshlrev_b64 v[32:33], 11, v[32:33]
	v_lshlrev_b32_e32 v34, 3, v143
	v_lshl_add_u64 v[32:33], s[20:21], 0, v[32:33]
	s_lshl_b32 s28, s35, 8
	v_and_b32_e32 v76, 0x78, v34
	v_lshl_add_u64 v[32:33], v[32:33], 0, s[28:29]
	v_lshlrev_b32_e32 v140, 1, v76
	v_lshl_add_u64 v[32:33], v[32:33], 0, v[140:141]
	v_lshlrev_b32_e32 v160, 2, v76
	global_load_dwordx4 v[40:43], v[32:33], off
	s_nop 0
	global_load_dwordx4 v[32:35], v160, s[14:15] offset:16
	global_load_dwordx4 v[36:39], v160, s[14:15]
	s_lshl_b32 s28, s35, 7
	v_cmp_gt_i32_e32 vcc, s50, v143
	s_and_saveexec_b64 s[46:47], vcc
	s_cbranch_execz .LBB0_948
	v_mul_hi_i32 v77, v142, s51
	v_lshrrev_b32_e32 v78, 31, v77
	v_add_u32_e32 v154, v77, v78
	v_lshl_add_u32 v77, v154, 1, v154
	v_sub_u32_e32 v166, v142, v77
	v_lshlrev_b32_e32 v77, 10, v166
	v_or3_b32 v156, v77, s28, v76
	v_ashrrev_i32_e32 v157, 31, v156
	v_cmp_lt_i32_e32 vcc, 8, v142
	s_and_saveexec_b64 s[4:5], vcc
	s_xor_b64 s[4:5], exec, s[4:5]
	s_cbranch_execz .LBB0_929
	v_mov_b32_e32 v155, v141
	v_lshl_add_u64 v[76:77], v[154:155], 0, s[42:43]
	v_mov_b64_e32 v[78:79], s[6:7]
	v_mad_u64_u32 v[78:79], s[48:49], v76, s52, v[78:79]
	v_mad_i32_i24 v79, v77, s52, v79
	v_lshl_add_u64 v[76:77], v[156:157], 1, v[78:79]
	v_add_co_u32_e32 v76, vcc, 0xffffc000, v76
	s_nop 1
	v_addc_co_u32_e32 v77, vcc, -1, v77, vcc
	global_load_dwordx4 v[76:79], v[76:77], off offset:-2048
	s_waitcnt vmcnt(0)
	v_lshlrev_b32_e32 v80, 16, v76
	v_and_b32_e32 v81, 0xffff0000, v76
	v_lshlrev_b32_e32 v82, 16, v77
	v_and_b32_e32 v83, 0xffff0000, v77
	v_lshlrev_b32_e32 v76, 16, v78
	v_and_b32_e32 v77, 0xffff0000, v78
	v_lshlrev_b32_e32 v78, 16, v79
	v_and_b32_e32 v79, 0xffff0000, v79

.LBB0_948:
	s_or_b64 exec, exec, s[46:47]
	v_and_b32_e32 v76, 0xffffffe0, v143
	s_waitcnt lgkmcnt(0)
	s_barrier
	v_add_u32_e32 v80, 0, v76
	s_waitcnt vmcnt(10)
	s_cmp_lt_i32 s100, 0
	s_cbranch_scc1 .Lmy_nopf
	s_lshl_b64 s[98:99], s[100:101], 16
	s_add_u32 s98, s10, s98
	s_addc_u32 s99, s11, s99
	v_lshlrev_b64 v[174:175], 9, v[144:145]
	v_lshl_add_u64 v[174:175], s[98:99], 0, v[174:175]
	v_lshlrev_b32_e32 v176, 4, v159
	v_mov_b32_e32 v177, 0
	v_lshl_add_u64 v[174:175], v[174:175], 0, v[176:177]
	global_load_dwordx4 v[28:31], v[174:175], off nt
	global_load_dwordx4 v[24:27], v[174:175], off offset:512 nt
	global_load_dwordx4 v[20:23], v[174:175], off offset:1024 nt
	global_load_dwordx4 v[16:19], v[174:175], off offset:1536 nt
	global_load_dwordx4 v[12:15], v[174:175], off offset:2048 nt
	global_load_dwordx4 v[8:11], v[174:175], off offset:2560 nt
	global_load_dwordx4 v[4:7], v[174:175], off offset:3072 nt
	global_load_dwordx4 v[0:3], v[174:175], off offset:3584 nt
	s_branch .Lmy_pfj

.Lmy_pfj:
	v_mul_f32_e32 v76, 0x3fb8aa3b, v165
	v_exp_f32_e32 v86, v76
	ds_read_b128 v[82:85], v80 offset:2048
	v_lshl_add_u32 v78, v159, 4, 0
	v_lshl_add_u32 v76, v164, 9, v78
	v_pk_mul_f32 v[88:89], v[74:75], v[86:87] op_sel_hi:[1,0]
	v_pk_mul_f32 v[90:91], v[72:73], v[86:87] op_sel_hi:[1,0]
	ds_read_b128 v[72:75], v80 offset:2064
	s_waitcnt lgkmcnt(1)
	v_pk_fma_f32 v[92:93], v[90:91], v[82:83], 0 op_sel_hi:[1,0,0]
	v_pk_fma_f32 v[94:95], v[88:89], v[82:83], 0 op_sel_hi:[1,0,0]
	v_pk_mul_f32 v[96:97], v[70:71], v[86:87] op_sel_hi:[1,0]
	v_pk_mul_f32 v[68:69], v[68:69], v[86:87] op_sel_hi:[1,0]
	v_pk_fma_f32 v[70:71], v[96:97], v[82:83], v[94:95] op_sel:[0,1,0]
	v_pk_fma_f32 v[82:83], v[68:69], v[82:83], v[92:93] op_sel:[0,1,0]
	v_pk_mul_f32 v[66:67], v[66:67], v[86:87] op_sel_hi:[1,0]
	v_pk_mul_f32 v[92:93], v[64:65], v[86:87] op_sel_hi:[1,0]
	v_pk_fma_f32 v[64:65], v[66:67], v[84:85], v[70:71] op_sel_hi:[1,0,1]
	v_pk_fma_f32 v[70:71], v[92:93], v[84:85], v[82:83] op_sel_hi:[1,0,1]
	v_pk_mul_f32 v[62:63], v[62:63], v[86:87] op_sel_hi:[1,0]
	v_pk_mul_f32 v[94:95], v[60:61], v[86:87] op_sel_hi:[1,0]
	v_mov_b32_e32 v60, v85
	v_pk_fma_f32 v[64:65], v[62:63], v[60:61], v[64:65] op_sel_hi:[1,0,1]
	v_pk_fma_f32 v[60:61], v[94:95], v[60:61], v[70:71] op_sel_hi:[1,0,1]
	v_pk_mul_f32 v[98:99], v[58:59], v[86:87] op_sel_hi:[1,0]
	v_pk_mul_f32 v[100:101], v[56:57], v[86:87] op_sel_hi:[1,0]
	s_waitcnt lgkmcnt(0)
	v_pk_fma_f32 v[56:57], v[98:99], v[72:73], v[64:65] op_sel_hi:[1,0,1]
	v_pk_fma_f32 v[58:59], v[100:101], v[72:73], v[60:61] op_sel_hi:[1,0,1]
	v_pk_mul_f32 v[102:103], v[54:55], v[86:87] op_sel_hi:[1,0]
	v_pk_mul_f32 v[104:105], v[52:53], v[86:87] op_sel_hi:[1,0]
	v_pk_fma_f32 v[52:53], v[102:103], v[72:73], v[56:57] op_sel:[0,1,0]
	v_pk_fma_f32 v[54:55], v[104:105], v[72:73], v[58:59] op_sel:[0,1,0]
	v_pk_mul_f32 v[106:107], v[50:51], v[86:87] op_sel_hi:[1,0]
	v_pk_mul_f32 v[108:109], v[48:49], v[86:87] op_sel_hi:[1,0]
	v_pk_fma_f32 v[48:49], v[106:107], v[74:75], v[52:53] op_sel_hi:[1,0,1]
	v_pk_fma_f32 v[50:51], v[108:109], v[74:75], v[54:55] op_sel_hi:[1,0,1]
	v_pk_mul_f32 v[110:111], v[46:47], v[86:87] op_sel_hi:[1,0]
	v_pk_mul_f32 v[112:113], v[44:45], v[86:87] op_sel_hi:[1,0]
	v_mov_b32_e32 v44, v75
	v_pk_fma_f32 v[46:47], v[110:111], v[44:45], v[48:49] op_sel_hi:[1,0,1]
	v_pk_fma_f32 v[44:45], v[112:113], v[44:45], v[50:51] op_sel_hi:[1,0,1]
	ds_write_b128 v76, v[44:47] offset:8192
	s_waitcnt lgkmcnt(0)
	s_barrier
	ds_read_b128 v[44:47], v78 offset:8192
	ds_read_b128 v[48:51], v78 offset:8704
	ds_read_b128 v[52:55], v78 offset:4096
	ds_read_b128 v[56:59], v78 offset:9216
	v_lshl_add_u32 v79, v164, 5, 0
	v_lshl_add_u32 v77, v143, 2, 0
	s_waitcnt lgkmcnt(3)
	v_pk_add_f32 v[46:47], v[46:47], 0 op_sel_hi:[1,0]
	v_pk_add_f32 v[60:61], v[44:45], 0 op_sel_hi:[1,0]
	s_waitcnt lgkmcnt(2)
	v_pk_add_f32 v[50:51], v[46:47], v[50:51]
	ds_read_b128 v[44:47], v78 offset:9728
	v_pk_add_f32 v[60:61], v[60:61], v[48:49]
	s_waitcnt lgkmcnt(1)
	v_pk_add_f32 v[58:59], v[50:51], v[58:59]
	ds_read_b128 v[48:51], v78 offset:10240
	v_pk_add_f32 v[60:61], v[60:61], v[56:57]
	s_waitcnt lgkmcnt(1)
	v_pk_add_f32 v[46:47], v[58:59], v[46:47]
	ds_read_b128 v[56:59], v78 offset:10752
	v_pk_add_f32 v[60:61], v[60:61], v[44:45]
	s_waitcnt lgkmcnt(1)
	v_pk_add_f32 v[50:51], v[46:47], v[50:51]
	ds_read_b128 v[44:47], v78 offset:11264
	v_pk_add_f32 v[60:61], v[60:61], v[48:49]
	s_waitcnt lgkmcnt(1)
	v_pk_add_f32 v[58:59], v[50:51], v[58:59]
	ds_read_b128 v[48:51], v78 offset:11776
	v_pk_add_f32 v[60:61], v[60:61], v[56:57]
	s_waitcnt lgkmcnt(1)
	v_pk_add_f32 v[46:47], v[58:59], v[46:47]
	ds_read_b128 v[56:59], v78 offset:12288
	v_pk_add_f32 v[60:61], v[60:61], v[44:45]
	s_waitcnt lgkmcnt(1)
	v_pk_add_f32 v[50:51], v[46:47], v[50:51]
	ds_read_b128 v[44:47], v78 offset:12800
	v_pk_add_f32 v[60:61], v[60:61], v[48:49]
	s_waitcnt lgkmcnt(1)
	v_pk_add_f32 v[58:59], v[50:51], v[58:59]
	ds_read_b128 v[48:51], v78 offset:13312
	v_pk_add_f32 v[60:61], v[60:61], v[56:57]
	s_waitcnt lgkmcnt(1)
	v_pk_add_f32 v[46:47], v[58:59], v[46:47]
	ds_read_b128 v[56:59], v78 offset:13824
	v_pk_add_f32 v[60:61], v[60:61], v[44:45]
	s_waitcnt lgkmcnt(1)
	v_pk_add_f32 v[50:51], v[46:47], v[50:51]
	ds_read_b128 v[44:47], v78 offset:14336
	v_pk_add_f32 v[60:61], v[60:61], v[48:49]
	s_waitcnt lgkmcnt(1)
	v_pk_add_f32 v[58:59], v[50:51], v[58:59]
	ds_read_b128 v[48:51], v78 offset:14848
	v_pk_add_f32 v[60:61], v[60:61], v[56:57]
	s_waitcnt lgkmcnt(1)
	v_pk_add_f32 v[46:47], v[58:59], v[46:47]
	ds_read_b128 v[56:59], v78 offset:15360
	v_pk_add_f32 v[44:45], v[60:61], v[44:45]
	s_waitcnt lgkmcnt(1)
	v_pk_add_f32 v[50:51], v[46:47], v[50:51]
	v_pk_add_f32 v[48:49], v[44:45], v[48:49]
	ds_read_b128 v[44:47], v78 offset:15872
	s_waitcnt lgkmcnt(1)
	v_pk_add_f32 v[50:51], v[50:51], v[58:59]
	v_pk_add_f32 v[48:49], v[48:49], v[56:57]
	ds_read_b128 v[56:59], v79
	ds_read_b128 v[82:85], v79 offset:16
	s_waitcnt lgkmcnt(2)
	v_pk_add_f32 v[46:47], v[50:51], v[46:47]
	v_pk_add_f32 v[48:49], v[48:49], v[44:45]
	v_sub_f32_e32 v51, v55, v47
	v_sub_f32_e32 v50, v54, v46
	ds_read_b128 v[44:47], v79 offset:2048
	v_sub_f32_e32 v49, v53, v49
	v_sub_f32_e32 v48, v52, v48
	s_waitcnt vmcnt(11)
	v_pk_mul_f32 v[52:53], v[152:153], v[50:51] op_sel_hi:[0,1]
	v_pk_mul_f32 v[114:115], v[152:153], v[48:49] op_sel_hi:[0,1]
	s_waitcnt lgkmcnt(0)
	v_pk_fma_f32 v[70:71], v[52:53], v[44:45], v[88:89] op_sel_hi:[1,0,1]
	ds_read_b128 v[86:89], v79 offset:2064
	v_pk_fma_f32 v[72:73], v[114:115], v[44:45], v[90:91] op_sel_hi:[1,0,1]
	v_pk_fma_f32 v[48:49], v[56:57], v[70:71], 0 op_sel_hi:[0,1,0]
	v_pk_fma_f32 v[50:51], v[56:57], v[72:73], 0 op_sel_hi:[0,1,0]
	v_pk_fma_f32 v[60:61], v[52:53], v[44:45], v[96:97] op_sel:[0,1,0]
	v_pk_fma_f32 v[64:65], v[114:115], v[44:45], v[68:69] op_sel:[0,1,0]
	v_pk_fma_f32 v[44:45], v[56:57], v[60:61], v[48:49] op_sel:[1,0,0]
	v_pk_fma_f32 v[48:49], v[56:57], v[64:65], v[50:51] op_sel:[1,0,0]
	v_pk_fma_f32 v[50:51], v[52:53], v[46:47], v[66:67] op_sel_hi:[1,0,1]
	v_pk_fma_f32 v[56:57], v[114:115], v[46:47], v[92:93] op_sel_hi:[1,0,1]
	v_mov_b32_e32 v46, v47
	v_pk_fma_f32 v[44:45], v[58:59], v[50:51], v[44:45] op_sel_hi:[0,1,1]
	v_pk_fma_f32 v[54:55], v[58:59], v[56:57], v[48:49] op_sel_hi:[0,1,1]
	v_pk_fma_f32 v[48:49], v[52:53], v[46:47], v[62:63] op_sel_hi:[1,0,1]
	v_pk_fma_f32 v[74:75], v[114:115], v[46:47], v[94:95] op_sel_hi:[1,0,1]
	v_mov_b32_e32 v46, v59
	v_pk_fma_f32 v[44:45], v[46:47], v[48:49], v[44:45] op_sel_hi:[0,1,1]
	v_pk_fma_f32 v[46:47], v[46:47], v[74:75], v[54:55] op_sel_hi:[0,1,1]
	s_waitcnt lgkmcnt(0)
	v_pk_fma_f32 v[66:67], v[52:53], v[86:87], v[98:99] op_sel_hi:[1,0,1]
	v_pk_fma_f32 v[68:69], v[114:115], v[86:87], v[100:101] op_sel_hi:[1,0,1]
	v_pk_fma_f32 v[44:45], v[82:83], v[66:67], v[44:45] op_sel_hi:[0,1,1]
	v_pk_fma_f32 v[46:47], v[82:83], v[68:69], v[46:47] op_sel_hi:[0,1,1]
	v_pk_fma_f32 v[58:59], v[52:53], v[86:87], v[102:103] op_sel:[0,1,0]
	v_pk_fma_f32 v[62:63], v[114:115], v[86:87], v[104:105] op_sel:[0,1,0]
	v_pk_fma_f32 v[44:45], v[82:83], v[58:59], v[44:45] op_sel:[1,0,0]
	v_pk_fma_f32 v[82:83], v[82:83], v[62:63], v[46:47] op_sel:[1,0,0]
	v_pk_fma_f32 v[46:47], v[52:53], v[88:89], v[106:107] op_sel_hi:[1,0,1]
	v_pk_fma_f32 v[54:55], v[114:115], v[88:89], v[108:109] op_sel_hi:[1,0,1]
	v_pk_fma_f32 v[86:87], v[84:85], v[46:47], v[44:45] op_sel_hi:[0,1,1]
	v_pk_fma_f32 v[82:83], v[84:85], v[54:55], v[82:83] op_sel_hi:[0,1,1]
	v_mov_b32_e32 v84, v89
	v_pk_fma_f32 v[44:45], v[52:53], v[84:85], v[110:111] op_sel_hi:[1,0,1]
	v_pk_fma_f32 v[52:53], v[114:115], v[84:85], v[112:113] op_sel_hi:[1,0,1]
	v_mov_b32_e32 v88, v85
	v_pk_fma_f32 v[84:85], v[88:89], v[44:45], v[86:87] op_sel_hi:[0,1,1]
	v_pk_fma_f32 v[82:83], v[88:89], v[52:53], v[82:83] op_sel_hi:[0,1,1]
	s_waitcnt lgkmcnt(0)
	s_barrier
	ds_write_b128 v76, v[82:85] offset:8192
	s_waitcnt lgkmcnt(0)
	s_barrier
	v_cmp_gt_i32_e32 vcc, s55, v143
	s_and_saveexec_b64 s[4:5], vcc
	s_cbranch_execz .LBB0_950
	ds_read2st64_b32 v[82:83], v77 offset0:32 offset1:34
	ds_read2st64_b32 v[84:85], v77 offset0:36 offset1:38
	ds_read2st64_b32 v[86:87], v77 offset0:40 offset1:42
	ds_read2st64_b32 v[88:89], v77 offset0:44 offset1:46
	ds_read2st64_b32 v[90:91], v77 offset0:48 offset1:50
	s_waitcnt lgkmcnt(4)
	v_add_f32_e32 v81, 0, v82
	v_add_f32_e32 v81, v81, v83
	s_waitcnt lgkmcnt(3)
	v_add_f32_e32 v81, v81, v84
	v_add_f32_e32 v81, v81, v85
	s_waitcnt lgkmcnt(2)
	v_add_f32_e32 v81, v81, v86
	v_add_f32_e32 v81, v81, v87
	ds_read2st64_b32 v[82:83], v77 offset0:52 offset1:54
	s_waitcnt lgkmcnt(2)
	v_add_f32_e32 v81, v81, v88
	v_add_f32_e32 v81, v81, v89
	ds_read2st64_b32 v[84:85], v77 offset0:56 offset1:58
	s_waitcnt lgkmcnt(2)
	v_add_f32_e32 v81, v81, v90
	v_add_f32_e32 v81, v81, v91
	ds_read2st64_b32 v[86:87], v77 offset0:60 offset1:62
	s_waitcnt lgkmcnt(2)
	v_add_f32_e32 v81, v81, v82
	v_add_f32_e32 v81, v81, v83
	s_waitcnt lgkmcnt(1)
	v_add_f32_e32 v81, v81, v84
	v_add_f32_e32 v81, v81, v85
	s_waitcnt lgkmcnt(0)
	v_add_f32_e32 v81, v81, v86
	v_add_f32_e32 v81, v81, v87
	ds_write_b32 v77, v81 offset:6144

.LBB0_956:
	s_or_b64 exec, exec, s[4:5]
	s_waitcnt lgkmcnt(0)
	s_barrier
	v_lshlrev_b64 v[76:77], 9, v[144:145]
	v_lshl_or_b32 v76, v159, 4, v76
	v_lshl_add_u64 v[76:77], s[24:25], 0, v[76:77]
	v_cmp_gt_i32_e32 vcc, 64, v143
	global_store_dwordx4 v[76:77], v[44:47], off nt
	global_store_dwordx4 v[76:77], v[48:51], off offset:512 nt
	global_store_dwordx4 v[76:77], v[52:55], off offset:1024 nt
	global_store_dwordx4 v[76:77], v[56:59], off offset:1536 nt
	global_store_dwordx4 v[76:77], v[60:63], off offset:2048 nt
	global_store_dwordx4 v[76:77], v[64:67], off offset:2560 nt
	global_store_dwordx4 v[76:77], v[68:71], off offset:3072 nt
	global_store_dwordx4 v[76:77], v[72:75], off offset:3584 nt
	s_and_saveexec_b64 s[4:5], vcc
	s_cbranch_execz .LBB0_923
	v_lshlrev_b32_e32 v44, 9, v142
	v_add3_u32 v48, 0, v44, v160
	v_and_b32_e32 v44, 64, v149
	v_add_u32_e32 v60, 64, v44
	ds_read_b128 v[44:47], v48 offset:6144
	ds_read_b128 v[48:51], v48 offset:6160
	v_xor_b32_e32 v52, 1, v149
	v_cmp_lt_i32_e32 vcc, v52, v60
	v_xor_b32_e32 v62, 2, v149
	s_waitcnt lgkmcnt(1)
	v_pk_mul_f32 v[58:59], v[44:45], v[44:45]
	v_pk_mul_f32 v[56:57], v[46:47], v[46:47]
	v_add_f32_e32 v58, v58, v59
	v_add_f32_e32 v56, v58, v56
	s_waitcnt lgkmcnt(0)
	v_pk_mul_f32 v[54:55], v[48:49], v[48:49]
	v_add_f32_e32 v56, v56, v57
	v_cndmask_b32_e32 v52, v149, v52, vcc
	v_add_f32_e32 v54, v56, v54
	v_lshlrev_b32_e32 v61, 2, v52
	v_pk_mul_f32 v[52:53], v[50:51], v[50:51]
	v_add_f32_e32 v54, v54, v55
	v_add_f32_e32 v52, v54, v52
	v_add_f32_e32 v52, v52, v53
	ds_bpermute_b32 v53, v61, v52
	v_cmp_lt_i32_e32 vcc, v62, v60
	v_xor_b32_e32 v55, 4, v149
	v_ashrrev_i32_e32 v143, 31, v142
	v_cndmask_b32_e32 v54, v149, v62, vcc
	v_lshlrev_b32_e32 v54, 2, v54
	s_waitcnt lgkmcnt(0)
	v_add_f32_e32 v52, v52, v53
	ds_bpermute_b32 v53, v54, v52
	v_cmp_lt_i32_e32 vcc, v55, v60
	s_lshl_b32 s28, s28, 1
	s_waitcnt lgkmcnt(0)
	v_add_f32_e32 v53, v52, v53
	v_cndmask_b32_e32 v54, v149, v55, vcc
	v_lshlrev_b32_e32 v54, 2, v54
	ds_bpermute_b32 v54, v54, v53
	v_xor_b32_e32 v55, 8, v149
	v_cmp_lt_i32_e32 vcc, v55, v60
	s_waitcnt lgkmcnt(0)
	v_add_f32_e32 v56, v53, v54
	v_cndmask_b32_e32 v52, v149, v55, vcc
	v_lshlrev_b32_e32 v55, 2, v52
	ds_bpermute_b32 v57, v55, v56
	s_waitcnt vmcnt(18)
	v_lshlrev_b32_e32 v52, 16, v43
	v_and_b32_e32 v53, 0xffff0000, v43
	v_lshlrev_b32_e32 v54, 16, v42
	v_and_b32_e32 v55, 0xffff0000, v42
	s_waitcnt lgkmcnt(0)
	v_add_f32_e32 v43, v56, v57
	v_fmamk_f32 v43, v43, 0x3c000000, v147
	v_mul_f32_e32 v56, 0x4b800000, v43
	v_cmp_gt_f32_e32 vcc, s54, v43
	v_and_b32_e32 v57, 0xffff0000, v40
	v_lshlrev_b32_e32 v42, 16, v41
	v_cndmask_b32_e32 v43, v43, v56, vcc
	v_rsq_f32_e32 v58, v43
	v_lshlrev_b32_e32 v56, 16, v40
	v_and_b32_e32 v43, 0xffff0000, v41
	v_mul_f32_e32 v40, 0x45800000, v58
	v_cndmask_b32_e32 v40, v58, v40, vcc
	v_pk_mul_f32 v[44:45], v[44:45], v[40:41] op_sel_hi:[1,0]
	s_waitcnt vmcnt(16)
	v_pk_mul_f32 v[36:37], v[36:37], v[44:45]
	v_pk_mul_f32 v[44:45], v[46:47], v[40:41] op_sel_hi:[1,0]
	v_pk_mul_f32 v[36:37], v[36:37], v[56:57]
	v_pk_mul_f32 v[38:39], v[38:39], v[44:45]
	s_nop 0
	v_pk_mul_f32 v[38:39], v[38:39], v[42:43]
	v_pk_mul_f32 v[42:43], v[48:49], v[40:41] op_sel_hi:[1,0]
	s_nop 0
	v_pk_mul_f32 v[32:33], v[32:33], v[42:43]
	s_nop 0
	v_pk_mul_f32 v[42:43], v[32:33], v[54:55]
	v_pk_mul_f32 v[32:33], v[50:51], v[40:41] op_sel_hi:[1,0]
	s_nop 0
	v_pk_mul_f32 v[32:33], v[34:35], v[32:33]
	v_cvt_pk_bf16_f32 v34, v42, v43
	v_pk_mul_f32 v[40:41], v[32:33], v[52:53]
	v_cvt_pk_bf16_f32 v32, v36, v37
	v_cvt_pk_bf16_f32 v33, v38, v39
	v_lshl_add_u64 v[36:37], s[42:43], 0, v[142:143]
	v_mov_b64_e32 v[38:39], s[6:7]
	v_mad_u64_u32 v[38:39], s[34:35], v36, s52, v[38:39]
	v_mad_i32_i24 v39, v37, s52, v39
	v_lshl_add_u64 v[36:37], v[38:39], 0, s[28:29]
	v_lshl_add_u64 v[36:37], v[36:37], 0, v[140:141]
	v_add_co_u32_e32 v36, vcc, 0x1000, v36
	v_cvt_pk_bf16_f32 v35, v40, v41
	s_nop 0
	v_addc_co_u32_e32 v37, vcc, 0, v37, vcc
	global_store_dwordx4 v[36:37], v[32:35], off
	s_branch .LBB0_923
